# v010
# speedup vs baseline: 1.0082x; 1.0078x over previous
; #define SCHED __builtin_amdgcn_sched_barrier(0)
; __device__ __forceinline__ void residual_epi(ACC_T, const float* __restrict__ xs, float* __restrict__ xo, float alpha,
;                                              int brow, int bcol, int wr, int wc, int fr, int fq) {
; #pragma unroll
;   for (int ai = 0; ai < 2; ++ai)
; #pragma unroll
;     for (int bj = 0; bj < 2; ++bj) {
;       float4 t[4][2];
;       size_t base = (size_t)(brow + ai * 128 + wr * 64 + fr) * 2048 + (bcol + bj * 128 + wc * 32 + fq * 4);
; #pragma unroll
;       for (int m = 0; m < 4; ++m)
; #pragma unroll
;         for (int n = 0; n < 2; ++n) t[m][n] = *(const float4*)(xs + base + (size_t)(m * 16) * 2048 + n * 16);
;       SCHED;
; #pragma unroll
;       for (int m = 0; m < 4; ++m)
; #pragma unroll
;         for (int n = 0; n < 2; ++n) {
;           f32x4 a = acc[ai][bj][m][n];
;           float4 o; o.x = t[m][n].x + alpha * a[0]; o.y = t[m][n].y + alpha * a[1]; o.z = t[m][n].z + alpha * a[2]; o.w = t[m][n].w + alpha * a[3];
;           *(float4*)(xo + base + (size_t)(m * 16) * 2048 + n * 16) = o;
.LBB0_918:
	v_ashrrev_i32_e32 v128, 2, v138
	v_and_b32_e32 v128, 0xffffffc0, v128
	v_add_u32_e32 v128, s21, v128
	v_lshrrev_b32_e32 v129, 1, v138
	v_lshrrev_b32_e32 v130, 2, v138
	v_and_or_b32 v128, v138, 15, v128
	v_and_b32_e32 v129, 0x60, v129
	v_and_b32_e32 v130, 12, v130
	v_or3_b32 v130, v129, v130, s22
	v_ashrrev_i32_e32 v129, 31, v128
	v_ashrrev_i32_e32 v131, 31, v130
	v_lshlrev_b64 v[132:133], 13, v[128:129]
	v_lshlrev_b64 v[130:131], 2, v[130:131]
	v_lshl_add_u64 v[132:133], v[132:133], 0, v[130:131]
	v_lshl_add_u64 v[134:135], s[4:5], 0, v[132:133]
	v_lshl_add_u64 v[136:137], s[8:9], 0, v[132:133]
	v_add_co_u32_e32 v140, vcc, 0x20000, v134
	s_nop 1
	v_addc_co_u32_e32 v141, vcc, 0, v135, vcc
	v_add_co_u32_e32 v144, vcc, 0x40000, v134
	s_nop 1
	v_addc_co_u32_e32 v145, vcc, 0, v135, vcc
	v_add_co_u32_e32 v128, vcc, 0x60000, v134
	s_nop 1
	v_addc_co_u32_e32 v129, vcc, 0, v135, vcc
	v_add_co_u32_e32 v142, vcc, 0x20000, v136
	s_nop 1
	v_addc_co_u32_e32 v143, vcc, 0, v137, vcc
	v_add_co_u32_e32 v146, vcc, 0x40000, v136
	s_nop 1
	v_addc_co_u32_e32 v147, vcc, 0, v137, vcc
	v_add_co_u32_e32 v130, vcc, 0x60000, v136
	s_nop 1
	v_addc_co_u32_e32 v131, vcc, 0, v137, vcc
	global_load_dwordx4 v[180:183], v[134:135], off offset:0
	global_load_dwordx4 v[184:187], v[134:135], off offset:64
	global_load_dwordx4 v[188:191], v[140:141], off offset:0
	global_load_dwordx4 v[192:195], v[140:141], off offset:64
	global_load_dwordx4 v[196:199], v[144:145], off offset:0
	global_load_dwordx4 v[200:203], v[144:145], off offset:64
	global_load_dwordx4 v[204:207], v[128:129], off offset:0
	global_load_dwordx4 v[208:211], v[128:129], off offset:64
	global_load_dwordx4 v[158:161], v[134:135], off offset:512
	global_load_dwordx4 v[162:165], v[134:135], off offset:576
	global_load_dwordx4 v[166:169], v[140:141], off offset:512
	global_load_dwordx4 v[170:173], v[140:141], off offset:576
	global_load_dwordx4 v[212:215], v[144:145], off offset:512
	global_load_dwordx4 v[216:219], v[144:145], off offset:576
	global_load_dwordx4 v[238:241], v[128:129], off offset:512
	global_load_dwordx4 v[242:245], v[128:129], off offset:576
	s_waitcnt vmcnt(8)
	v_pk_fma_f32 v[124:125], v[124:125], 0.5, v[180:181] op_sel_hi:[1,0,1]
	v_pk_fma_f32 v[126:127], v[126:127], 0.5, v[182:183] op_sel_hi:[1,0,1]
	v_pk_fma_f32 v[120:121], v[120:121], 0.5, v[184:185] op_sel_hi:[1,0,1]
	v_pk_fma_f32 v[122:123], v[122:123], 0.5, v[186:187] op_sel_hi:[1,0,1]
	v_pk_fma_f32 v[116:117], v[116:117], 0.5, v[188:189] op_sel_hi:[1,0,1]
	v_pk_fma_f32 v[118:119], v[118:119], 0.5, v[190:191] op_sel_hi:[1,0,1]
	v_pk_fma_f32 v[112:113], v[112:113], 0.5, v[192:193] op_sel_hi:[1,0,1]
	v_pk_fma_f32 v[114:115], v[114:115], 0.5, v[194:195] op_sel_hi:[1,0,1]
	v_pk_fma_f32 v[108:109], v[108:109], 0.5, v[196:197] op_sel_hi:[1,0,1]
	v_pk_fma_f32 v[110:111], v[110:111], 0.5, v[198:199] op_sel_hi:[1,0,1]
	v_pk_fma_f32 v[104:105], v[104:105], 0.5, v[200:201] op_sel_hi:[1,0,1]
	v_pk_fma_f32 v[106:107], v[106:107], 0.5, v[202:203] op_sel_hi:[1,0,1]
	v_pk_fma_f32 v[100:101], v[100:101], 0.5, v[204:205] op_sel_hi:[1,0,1]
	v_pk_fma_f32 v[102:103], v[102:103], 0.5, v[206:207] op_sel_hi:[1,0,1]
	v_pk_fma_f32 v[96:97], v[96:97], 0.5, v[208:209] op_sel_hi:[1,0,1]
	v_pk_fma_f32 v[98:99], v[98:99], 0.5, v[210:211] op_sel_hi:[1,0,1]
	global_store_dwordx4 v[136:137], v[124:127], off offset:0
	global_store_dwordx4 v[136:137], v[120:123], off offset:64
	global_store_dwordx4 v[142:143], v[116:119], off offset:0
	global_store_dwordx4 v[142:143], v[112:115], off offset:64
	global_store_dwordx4 v[146:147], v[108:111], off offset:0
	global_store_dwordx4 v[146:147], v[104:107], off offset:64
	global_store_dwordx4 v[130:131], v[100:103], off offset:0
	global_store_dwordx4 v[130:131], v[96:99], off offset:64
	v_add_co_u32_e32 v134, vcc, 0x100000, v134
	s_nop 1
	v_addc_co_u32_e32 v135, vcc, 0, v135, vcc
	v_add_co_u32_e32 v140, vcc, 0x100000, v140
	s_nop 1
	v_addc_co_u32_e32 v141, vcc, 0, v141, vcc
	v_add_co_u32_e32 v144, vcc, 0x100000, v144
	s_nop 1
	v_addc_co_u32_e32 v145, vcc, 0, v145, vcc
	v_add_co_u32_e32 v128, vcc, 0x100000, v128
	s_nop 1
	v_addc_co_u32_e32 v129, vcc, 0, v129, vcc
	global_load_dwordx4 v[180:183], v[134:135], off offset:0
	global_load_dwordx4 v[184:187], v[134:135], off offset:64
	global_load_dwordx4 v[188:191], v[140:141], off offset:0
	global_load_dwordx4 v[192:195], v[140:141], off offset:64
	global_load_dwordx4 v[196:199], v[144:145], off offset:0
	global_load_dwordx4 v[200:203], v[144:145], off offset:64
	global_load_dwordx4 v[204:207], v[128:129], off offset:0
	global_load_dwordx4 v[208:211], v[128:129], off offset:64
	s_waitcnt vmcnt(16)
; #define SCHED __builtin_amdgcn_sched_barrier(0)
; __device__ __forceinline__ void residual_epi(ACC_T, const float* __restrict__ xs, float* __restrict__ xo, float alpha,
;                                              int brow, int bcol, int wr, int wc, int fr, int fq) {
; #pragma unroll
;   for (int ai = 0; ai < 2; ++ai)
; #pragma unroll
;     for (int bj = 0; bj < 2; ++bj) {
;       float4 t[4][2];
;       size_t base = (size_t)(brow + ai * 128 + wr * 64 + fr) * 2048 + (bcol + bj * 128 + wc * 32 + fq * 4);
; #pragma unroll
;       for (int m = 0; m < 4; ++m)
; #pragma unroll
;         for (int n = 0; n < 2; ++n) t[m][n] = *(const float4*)(xs + base + (size_t)(m * 16) * 2048 + n * 16);
;       SCHED;
; #pragma unroll
;       for (int m = 0; m < 4; ++m)
; #pragma unroll
;         for (int n = 0; n < 2; ++n) {
;           f32x4 a = acc[ai][bj][m][n];
;           float4 o; o.x = t[m][n].x + alpha * a[0]; o.y = t[m][n].y + alpha * a[1]; o.z = t[m][n].z + alpha * a[2]; o.w = t[m][n].w + alpha * a[3];
;           *(float4*)(xo + base + (size_t)(m * 16) * 2048 + n * 16) = o;
;         }
;       SCHED;
;     }
; }
	v_pk_fma_f32 v[92:93], v[92:93], 0.5, v[158:159] op_sel_hi:[1,0,1]
	v_pk_fma_f32 v[94:95], v[94:95], 0.5, v[160:161] op_sel_hi:[1,0,1]
	v_pk_fma_f32 v[88:89], v[88:89], 0.5, v[162:163] op_sel_hi:[1,0,1]
	v_pk_fma_f32 v[90:91], v[90:91], 0.5, v[164:165] op_sel_hi:[1,0,1]
	v_pk_fma_f32 v[84:85], v[84:85], 0.5, v[166:167] op_sel_hi:[1,0,1]
	v_pk_fma_f32 v[86:87], v[86:87], 0.5, v[168:169] op_sel_hi:[1,0,1]
	v_pk_fma_f32 v[80:81], v[80:81], 0.5, v[170:171] op_sel_hi:[1,0,1]
	v_pk_fma_f32 v[82:83], v[82:83], 0.5, v[172:173] op_sel_hi:[1,0,1]
	v_pk_fma_f32 v[76:77], v[76:77], 0.5, v[212:213] op_sel_hi:[1,0,1]
	v_pk_fma_f32 v[78:79], v[78:79], 0.5, v[214:215] op_sel_hi:[1,0,1]
	v_pk_fma_f32 v[72:73], v[72:73], 0.5, v[216:217] op_sel_hi:[1,0,1]
	v_pk_fma_f32 v[74:75], v[74:75], 0.5, v[218:219] op_sel_hi:[1,0,1]
	v_pk_fma_f32 v[68:69], v[68:69], 0.5, v[238:239] op_sel_hi:[1,0,1]
	v_pk_fma_f32 v[70:71], v[70:71], 0.5, v[240:241] op_sel_hi:[1,0,1]
	v_pk_fma_f32 v[64:65], v[64:65], 0.5, v[242:243] op_sel_hi:[1,0,1]
	v_pk_fma_f32 v[66:67], v[66:67], 0.5, v[244:245] op_sel_hi:[1,0,1]
	global_store_dwordx4 v[136:137], v[92:95], off offset:512
	global_store_dwordx4 v[136:137], v[88:91], off offset:576
	global_store_dwordx4 v[142:143], v[84:87], off offset:512
	global_store_dwordx4 v[142:143], v[80:83], off offset:576
	global_store_dwordx4 v[146:147], v[76:79], off offset:512
	global_store_dwordx4 v[146:147], v[72:75], off offset:576
	global_store_dwordx4 v[130:131], v[68:71], off offset:512
	global_store_dwordx4 v[130:131], v[64:67], off offset:576
	global_load_dwordx4 v[158:161], v[134:135], off offset:512
	global_load_dwordx4 v[162:165], v[134:135], off offset:576
	global_load_dwordx4 v[166:169], v[140:141], off offset:512
	global_load_dwordx4 v[170:173], v[140:141], off offset:576
	global_load_dwordx4 v[212:215], v[144:145], off offset:512
	global_load_dwordx4 v[216:219], v[144:145], off offset:576
	global_load_dwordx4 v[238:241], v[128:129], off offset:512
	global_load_dwordx4 v[242:245], v[128:129], off offset:576
	v_add_co_u32_e32 v136, vcc, 0x100000, v136
	s_nop 1
	v_addc_co_u32_e32 v137, vcc, 0, v137, vcc
	v_add_co_u32_e32 v142, vcc, 0x100000, v142
	s_nop 1
	v_addc_co_u32_e32 v143, vcc, 0, v143, vcc
	v_add_co_u32_e32 v146, vcc, 0x100000, v146
	s_nop 1
	v_addc_co_u32_e32 v147, vcc, 0, v147, vcc
	v_add_co_u32_e32 v130, vcc, 0x100000, v130
	s_nop 1
	v_addc_co_u32_e32 v131, vcc, 0, v131, vcc
	s_waitcnt vmcnt(16)
	v_pk_fma_f32 v[60:61], v[60:61], 0.5, v[180:181] op_sel_hi:[1,0,1]
	v_pk_fma_f32 v[62:63], v[62:63], 0.5, v[182:183] op_sel_hi:[1,0,1]
	v_pk_fma_f32 v[56:57], v[56:57], 0.5, v[184:185] op_sel_hi:[1,0,1]
	v_pk_fma_f32 v[58:59], v[58:59], 0.5, v[186:187] op_sel_hi:[1,0,1]
	v_pk_fma_f32 v[52:53], v[52:53], 0.5, v[188:189] op_sel_hi:[1,0,1]
	v_pk_fma_f32 v[54:55], v[54:55], 0.5, v[190:191] op_sel_hi:[1,0,1]
	v_pk_fma_f32 v[48:49], v[48:49], 0.5, v[192:193] op_sel_hi:[1,0,1]
	v_pk_fma_f32 v[50:51], v[50:51], 0.5, v[194:195] op_sel_hi:[1,0,1]
	v_pk_fma_f32 v[44:45], v[44:45], 0.5, v[196:197] op_sel_hi:[1,0,1]
	v_pk_fma_f32 v[46:47], v[46:47], 0.5, v[198:199] op_sel_hi:[1,0,1]
	v_pk_fma_f32 v[40:41], v[40:41], 0.5, v[200:201] op_sel_hi:[1,0,1]
	v_pk_fma_f32 v[42:43], v[42:43], 0.5, v[202:203] op_sel_hi:[1,0,1]
	v_pk_fma_f32 v[36:37], v[36:37], 0.5, v[204:205] op_sel_hi:[1,0,1]
	v_pk_fma_f32 v[38:39], v[38:39], 0.5, v[206:207] op_sel_hi:[1,0,1]
	v_pk_fma_f32 v[32:33], v[32:33], 0.5, v[208:209] op_sel_hi:[1,0,1]
	v_pk_fma_f32 v[34:35], v[34:35], 0.5, v[210:211] op_sel_hi:[1,0,1]
	global_store_dwordx4 v[136:137], v[60:63], off offset:0
	global_store_dwordx4 v[136:137], v[56:59], off offset:64
	global_store_dwordx4 v[142:143], v[52:55], off offset:0
	global_store_dwordx4 v[142:143], v[48:51], off offset:64
	global_store_dwordx4 v[146:147], v[44:47], off offset:0
	global_store_dwordx4 v[146:147], v[40:43], off offset:64
	global_store_dwordx4 v[130:131], v[36:39], off offset:0
	global_store_dwordx4 v[130:131], v[32:35], off offset:64
	s_waitcnt vmcnt(8)
	v_pk_fma_f32 v[28:29], v[28:29], 0.5, v[158:159] op_sel_hi:[1,0,1]
	v_pk_fma_f32 v[30:31], v[30:31], 0.5, v[160:161] op_sel_hi:[1,0,1]
	v_pk_fma_f32 v[24:25], v[24:25], 0.5, v[162:163] op_sel_hi:[1,0,1]
	v_pk_fma_f32 v[26:27], v[26:27], 0.5, v[164:165] op_sel_hi:[1,0,1]
	v_pk_fma_f32 v[20:21], v[20:21], 0.5, v[166:167] op_sel_hi:[1,0,1]
	v_pk_fma_f32 v[22:23], v[22:23], 0.5, v[168:169] op_sel_hi:[1,0,1]
	v_pk_fma_f32 v[16:17], v[16:17], 0.5, v[170:171] op_sel_hi:[1,0,1]
	v_pk_fma_f32 v[18:19], v[18:19], 0.5, v[172:173] op_sel_hi:[1,0,1]
	v_pk_fma_f32 v[12:13], v[12:13], 0.5, v[212:213] op_sel_hi:[1,0,1]
	v_pk_fma_f32 v[14:15], v[14:15], 0.5, v[214:215] op_sel_hi:[1,0,1]
	v_pk_fma_f32 v[8:9], v[8:9], 0.5, v[216:217] op_sel_hi:[1,0,1]
	v_pk_fma_f32 v[10:11], v[10:11], 0.5, v[218:219] op_sel_hi:[1,0,1]
	v_pk_fma_f32 v[4:5], v[4:5], 0.5, v[238:239] op_sel_hi:[1,0,1]
	v_pk_fma_f32 v[6:7], v[6:7], 0.5, v[240:241] op_sel_hi:[1,0,1]
	v_pk_fma_f32 v[0:1], v[0:1], 0.5, v[242:243] op_sel_hi:[1,0,1]
	v_pk_fma_f32 v[2:3], v[2:3], 0.5, v[244:245] op_sel_hi:[1,0,1]
	global_store_dwordx4 v[136:137], v[28:31], off offset:512
	global_store_dwordx4 v[136:137], v[24:27], off offset:576
	global_store_dwordx4 v[142:143], v[20:23], off offset:512
	global_store_dwordx4 v[142:143], v[16:19], off offset:576
	global_store_dwordx4 v[146:147], v[12:15], off offset:512
	global_store_dwordx4 v[146:147], v[8:11], off offset:576
	global_store_dwordx4 v[130:131], v[4:7], off offset:512
	global_store_dwordx4 v[130:131], v[0:3], off offset:576
	s_mov_b32 s25, 0x60000
	s_mov_b32 s21, 0x20000
	s_mov_b32 s22, 0x40000
	s_andn2_b64 vcc, exec, s[14:15]
	s_mov_b32 s22, s24
	s_mov_b32 s21, s23
	s_cbranch_vccz .LBB0_927

; #define SCHED __builtin_amdgcn_sched_barrier(0)
; __device__ __forceinline__ void residual_epi(ACC_T, const float* __restrict__ xs, float* __restrict__ xo, float alpha,
;                                              int brow, int bcol, int wr, int wc, int fr, int fq) {
; #pragma unroll
;   for (int ai = 0; ai < 2; ++ai)
; #pragma unroll
;     for (int bj = 0; bj < 2; ++bj) {
;       float4 t[4][2];
;       size_t base = (size_t)(brow + ai * 128 + wr * 64 + fr) * 2048 + (bcol + bj * 128 + wc * 32 + fq * 4);
; #pragma unroll
;       for (int m = 0; m < 4; ++m)
; #pragma unroll
;         for (int n = 0; n < 2; ++n) t[m][n] = *(const float4*)(xs + base + (size_t)(m * 16) * 2048 + n * 16);
;       SCHED;
; #pragma unroll
;       for (int m = 0; m < 4; ++m)
; #pragma unroll
;         for (int n = 0; n < 2; ++n) {
;           f32x4 a = acc[ai][bj][m][n];
;           float4 o; o.x = t[m][n].x + alpha * a[0]; o.y = t[m][n].y + alpha * a[1]; o.z = t[m][n].z + alpha * a[2]; o.w = t[m][n].w + alpha * a[3];
;           *(float4*)(xo + base + (size_t)(m * 16) * 2048 + n * 16) = o;
.LBB0_2531:
	v_ashrrev_i32_e32 v128, 2, v138
	v_and_b32_e32 v128, 0xffffffc0, v128
	v_add_u32_e32 v128, s14, v128
	v_lshrrev_b32_e32 v129, 1, v138
	v_lshrrev_b32_e32 v130, 2, v138
	v_and_or_b32 v128, v138, 15, v128
	v_and_b32_e32 v129, 0x60, v129
	v_and_b32_e32 v130, 12, v130
	v_or3_b32 v130, v129, v130, s12
	v_ashrrev_i32_e32 v129, 31, v128
	v_ashrrev_i32_e32 v131, 31, v130
	v_lshlrev_b64 v[132:133], 13, v[128:129]
	v_lshlrev_b64 v[130:131], 2, v[130:131]
	v_lshl_add_u64 v[132:133], v[132:133], 0, v[130:131]
	v_lshl_add_u64 v[134:135], s[8:9], 0, v[132:133]
	v_lshl_add_u64 v[136:137], s[8:9], 0, v[132:133]
	v_add_co_u32_e32 v140, vcc, 0x20000, v134
	s_nop 1
	v_addc_co_u32_e32 v141, vcc, 0, v135, vcc
	v_add_co_u32_e32 v144, vcc, 0x40000, v134
	s_nop 1
	v_addc_co_u32_e32 v145, vcc, 0, v135, vcc
	v_add_co_u32_e32 v128, vcc, 0x60000, v134
	s_nop 1
	v_addc_co_u32_e32 v129, vcc, 0, v135, vcc
	v_add_co_u32_e32 v142, vcc, 0x20000, v136
	s_nop 1
	v_addc_co_u32_e32 v143, vcc, 0, v137, vcc
	v_add_co_u32_e32 v146, vcc, 0x40000, v136
	s_nop 1
	v_addc_co_u32_e32 v147, vcc, 0, v137, vcc
	v_add_co_u32_e32 v130, vcc, 0x60000, v136
	s_nop 1
	v_addc_co_u32_e32 v131, vcc, 0, v137, vcc
	global_load_dwordx4 v[180:183], v[134:135], off offset:0
	global_load_dwordx4 v[184:187], v[134:135], off offset:64
	global_load_dwordx4 v[188:191], v[140:141], off offset:0
	global_load_dwordx4 v[192:195], v[140:141], off offset:64
	global_load_dwordx4 v[196:199], v[144:145], off offset:0
	global_load_dwordx4 v[200:203], v[144:145], off offset:64
	global_load_dwordx4 v[204:207], v[128:129], off offset:0
	global_load_dwordx4 v[208:211], v[128:129], off offset:64
	global_load_dwordx4 v[158:161], v[134:135], off offset:512
	global_load_dwordx4 v[162:165], v[134:135], off offset:576
	global_load_dwordx4 v[166:169], v[140:141], off offset:512
	global_load_dwordx4 v[170:173], v[140:141], off offset:576
	global_load_dwordx4 v[212:215], v[144:145], off offset:512
	global_load_dwordx4 v[216:219], v[144:145], off offset:576
	global_load_dwordx4 v[222:225], v[128:129], off offset:512
	global_load_dwordx4 v[226:229], v[128:129], off offset:576
	s_waitcnt vmcnt(8)
	v_pk_add_f32 v[124:125], v[124:125], v[180:181]
	v_pk_add_f32 v[126:127], v[126:127], v[182:183]
	v_pk_add_f32 v[120:121], v[120:121], v[184:185]
	v_pk_add_f32 v[122:123], v[122:123], v[186:187]
	v_pk_add_f32 v[116:117], v[116:117], v[188:189]
	v_pk_add_f32 v[118:119], v[118:119], v[190:191]
	v_pk_add_f32 v[112:113], v[112:113], v[192:193]
	v_pk_add_f32 v[114:115], v[114:115], v[194:195]
	v_pk_add_f32 v[108:109], v[108:109], v[196:197]
	v_pk_add_f32 v[110:111], v[110:111], v[198:199]
	v_pk_add_f32 v[104:105], v[104:105], v[200:201]
	v_pk_add_f32 v[106:107], v[106:107], v[202:203]
	v_pk_add_f32 v[100:101], v[100:101], v[204:205]
	v_pk_add_f32 v[102:103], v[102:103], v[206:207]
	v_pk_add_f32 v[96:97], v[96:97], v[208:209]
	v_pk_add_f32 v[98:99], v[98:99], v[210:211]
	global_store_dwordx4 v[136:137], v[124:127], off offset:0
	global_store_dwordx4 v[136:137], v[120:123], off offset:64
	global_store_dwordx4 v[142:143], v[116:119], off offset:0
	global_store_dwordx4 v[142:143], v[112:115], off offset:64
	global_store_dwordx4 v[146:147], v[108:111], off offset:0
	global_store_dwordx4 v[146:147], v[104:107], off offset:64
	global_store_dwordx4 v[130:131], v[100:103], off offset:0
	global_store_dwordx4 v[130:131], v[96:99], off offset:64
	v_add_co_u32_e32 v134, vcc, 0x100000, v134
	s_nop 1
	v_addc_co_u32_e32 v135, vcc, 0, v135, vcc
	v_add_co_u32_e32 v140, vcc, 0x100000, v140
	s_nop 1
	v_addc_co_u32_e32 v141, vcc, 0, v141, vcc
	v_add_co_u32_e32 v144, vcc, 0x100000, v144
	s_nop 1
	v_addc_co_u32_e32 v145, vcc, 0, v145, vcc
	v_add_co_u32_e32 v128, vcc, 0x100000, v128
	s_nop 1
	v_addc_co_u32_e32 v129, vcc, 0, v129, vcc
	global_load_dwordx4 v[180:183], v[134:135], off offset:0
	global_load_dwordx4 v[184:187], v[134:135], off offset:64
	global_load_dwordx4 v[188:191], v[140:141], off offset:0
	global_load_dwordx4 v[192:195], v[140:141], off offset:64
	global_load_dwordx4 v[196:199], v[144:145], off offset:0
	global_load_dwordx4 v[200:203], v[144:145], off offset:64
	global_load_dwordx4 v[204:207], v[128:129], off offset:0
	global_load_dwordx4 v[208:211], v[128:129], off offset:64
	s_waitcnt vmcnt(16)
; #define SCHED __builtin_amdgcn_sched_barrier(0)
; __device__ __forceinline__ void residual_epi(ACC_T, const float* __restrict__ xs, float* __restrict__ xo, float alpha,
;                                              int brow, int bcol, int wr, int wc, int fr, int fq) {
; #pragma unroll
;   for (int ai = 0; ai < 2; ++ai)
; #pragma unroll
;     for (int bj = 0; bj < 2; ++bj) {
;       float4 t[4][2];
;       size_t base = (size_t)(brow + ai * 128 + wr * 64 + fr) * 2048 + (bcol + bj * 128 + wc * 32 + fq * 4);
; #pragma unroll
;       for (int m = 0; m < 4; ++m)
; #pragma unroll
;         for (int n = 0; n < 2; ++n) t[m][n] = *(const float4*)(xs + base + (size_t)(m * 16) * 2048 + n * 16);
;       SCHED;
; #pragma unroll
;       for (int m = 0; m < 4; ++m)
; #pragma unroll
;         for (int n = 0; n < 2; ++n) {
;           f32x4 a = acc[ai][bj][m][n];
;           float4 o; o.x = t[m][n].x + alpha * a[0]; o.y = t[m][n].y + alpha * a[1]; o.z = t[m][n].z + alpha * a[2]; o.w = t[m][n].w + alpha * a[3];
;           *(float4*)(xo + base + (size_t)(m * 16) * 2048 + n * 16) = o;
;         }
;       SCHED;
;     }
; }
	v_pk_add_f32 v[92:93], v[92:93], v[158:159]
	v_pk_add_f32 v[94:95], v[94:95], v[160:161]
	v_pk_add_f32 v[88:89], v[88:89], v[162:163]
	v_pk_add_f32 v[90:91], v[90:91], v[164:165]
	v_pk_add_f32 v[84:85], v[84:85], v[166:167]
	v_pk_add_f32 v[86:87], v[86:87], v[168:169]
	v_pk_add_f32 v[80:81], v[80:81], v[170:171]
	v_pk_add_f32 v[82:83], v[82:83], v[172:173]
	v_pk_add_f32 v[76:77], v[76:77], v[212:213]
	v_pk_add_f32 v[78:79], v[78:79], v[214:215]
	v_pk_add_f32 v[72:73], v[72:73], v[216:217]
	v_pk_add_f32 v[74:75], v[74:75], v[218:219]
	v_pk_add_f32 v[68:69], v[68:69], v[222:223]
	v_pk_add_f32 v[70:71], v[70:71], v[224:225]
	v_pk_add_f32 v[64:65], v[64:65], v[226:227]
	v_pk_add_f32 v[66:67], v[66:67], v[228:229]
	global_store_dwordx4 v[136:137], v[92:95], off offset:512
	global_store_dwordx4 v[136:137], v[88:91], off offset:576
	global_store_dwordx4 v[142:143], v[84:87], off offset:512
	global_store_dwordx4 v[142:143], v[80:83], off offset:576
	global_store_dwordx4 v[146:147], v[76:79], off offset:512
	global_store_dwordx4 v[146:147], v[72:75], off offset:576
	global_store_dwordx4 v[130:131], v[68:71], off offset:512
	global_store_dwordx4 v[130:131], v[64:67], off offset:576
	global_load_dwordx4 v[158:161], v[134:135], off offset:512
	global_load_dwordx4 v[162:165], v[134:135], off offset:576
	global_load_dwordx4 v[166:169], v[140:141], off offset:512
	global_load_dwordx4 v[170:173], v[140:141], off offset:576
	global_load_dwordx4 v[212:215], v[144:145], off offset:512
	global_load_dwordx4 v[216:219], v[144:145], off offset:576
	global_load_dwordx4 v[222:225], v[128:129], off offset:512
	global_load_dwordx4 v[226:229], v[128:129], off offset:576
	v_add_co_u32_e32 v136, vcc, 0x100000, v136
	s_nop 1
	v_addc_co_u32_e32 v137, vcc, 0, v137, vcc
	v_add_co_u32_e32 v142, vcc, 0x100000, v142
	s_nop 1
	v_addc_co_u32_e32 v143, vcc, 0, v143, vcc
	v_add_co_u32_e32 v146, vcc, 0x100000, v146
	s_nop 1
	v_addc_co_u32_e32 v147, vcc, 0, v147, vcc
	v_add_co_u32_e32 v130, vcc, 0x100000, v130
	s_nop 1
	v_addc_co_u32_e32 v131, vcc, 0, v131, vcc
	s_waitcnt vmcnt(16)
	v_pk_add_f32 v[60:61], v[60:61], v[180:181]
	v_pk_add_f32 v[62:63], v[62:63], v[182:183]
	v_pk_add_f32 v[56:57], v[56:57], v[184:185]
	v_pk_add_f32 v[58:59], v[58:59], v[186:187]
	v_pk_add_f32 v[52:53], v[52:53], v[188:189]
	v_pk_add_f32 v[54:55], v[54:55], v[190:191]
	v_pk_add_f32 v[48:49], v[48:49], v[192:193]
	v_pk_add_f32 v[50:51], v[50:51], v[194:195]
	v_pk_add_f32 v[44:45], v[44:45], v[196:197]
	v_pk_add_f32 v[46:47], v[46:47], v[198:199]
	v_pk_add_f32 v[40:41], v[40:41], v[200:201]
	v_pk_add_f32 v[42:43], v[42:43], v[202:203]
	v_pk_add_f32 v[36:37], v[36:37], v[204:205]
	v_pk_add_f32 v[38:39], v[38:39], v[206:207]
	v_pk_add_f32 v[32:33], v[32:33], v[208:209]
	v_pk_add_f32 v[34:35], v[34:35], v[210:211]
	global_store_dwordx4 v[136:137], v[60:63], off offset:0
	global_store_dwordx4 v[136:137], v[56:59], off offset:64
	global_store_dwordx4 v[142:143], v[52:55], off offset:0
	global_store_dwordx4 v[142:143], v[48:51], off offset:64
	global_store_dwordx4 v[146:147], v[44:47], off offset:0
	global_store_dwordx4 v[146:147], v[40:43], off offset:64
	global_store_dwordx4 v[130:131], v[36:39], off offset:0
	global_store_dwordx4 v[130:131], v[32:35], off offset:64
	s_waitcnt vmcnt(8)
	v_pk_add_f32 v[28:29], v[28:29], v[158:159]
	v_pk_add_f32 v[30:31], v[30:31], v[160:161]
	v_pk_add_f32 v[24:25], v[24:25], v[162:163]
	v_pk_add_f32 v[26:27], v[26:27], v[164:165]
	v_pk_add_f32 v[20:21], v[20:21], v[166:167]
	v_pk_add_f32 v[22:23], v[22:23], v[168:169]
	v_pk_add_f32 v[16:17], v[16:17], v[170:171]
	v_pk_add_f32 v[18:19], v[18:19], v[172:173]
	v_pk_add_f32 v[12:13], v[12:13], v[212:213]
	v_pk_add_f32 v[14:15], v[14:15], v[214:215]
	v_pk_add_f32 v[8:9], v[8:9], v[216:217]
	v_pk_add_f32 v[10:11], v[10:11], v[218:219]
	v_pk_add_f32 v[4:5], v[4:5], v[222:223]
	v_pk_add_f32 v[6:7], v[6:7], v[224:225]
	v_pk_add_f32 v[0:1], v[0:1], v[226:227]
	v_pk_add_f32 v[2:3], v[2:3], v[228:229]
	global_store_dwordx4 v[136:137], v[28:31], off offset:512
	global_store_dwordx4 v[136:137], v[24:27], off offset:576
	global_store_dwordx4 v[142:143], v[20:23], off offset:512
	global_store_dwordx4 v[142:143], v[16:19], off offset:576
	global_store_dwordx4 v[146:147], v[12:15], off offset:512
	global_store_dwordx4 v[146:147], v[8:11], off offset:576
	global_store_dwordx4 v[130:131], v[4:7], off offset:512
	global_store_dwordx4 v[130:131], v[0:3], off offset:576
	s_mov_b32 s13, 0x60000
	s_mov_b32 s12, 0x40000
	s_andn2_b64 vcc, exec, s[18:19]
	s_mov_b32 s12, s22
	s_mov_b32 s14, s20
	s_cbranch_vccz .LBB0_2540

; #define SCHED __builtin_amdgcn_sched_barrier(0)
; __device__ __forceinline__ void residual_epi(ACC_T, const float* __restrict__ xs, float* __restrict__ xo, float alpha,
;                                              int brow, int bcol, int wr, int wc, int fr, int fq) {
; #pragma unroll
;   for (int ai = 0; ai < 2; ++ai)
; #pragma unroll
;     for (int bj = 0; bj < 2; ++bj) {
;       float4 t[4][2];
;       size_t base = (size_t)(brow + ai * 128 + wr * 64 + fr) * 2048 + (bcol + bj * 128 + wc * 32 + fq * 4);
; #pragma unroll
;       for (int m = 0; m < 4; ++m)
; #pragma unroll
;         for (int n = 0; n < 2; ++n) t[m][n] = *(const float4*)(xs + base + (size_t)(m * 16) * 2048 + n * 16);
;       SCHED;
; #pragma unroll
;       for (int m = 0; m < 4; ++m)
; #pragma unroll
;         for (int n = 0; n < 2; ++n) {
;           f32x4 a = acc[ai][bj][m][n];
;           float4 o; o.x = t[m][n].x + alpha * a[0]; o.y = t[m][n].y + alpha * a[1]; o.z = t[m][n].z + alpha * a[2]; o.w = t[m][n].w + alpha * a[3];
;           *(float4*)(xo + base + (size_t)(m * 16) * 2048 + n * 16) = o;
.LBB0_2576:
	v_ashrrev_i32_e32 v128, 2, v138
	v_and_b32_e32 v128, 0xffffffc0, v128
	v_add_u32_e32 v128, s19, v128
	v_lshrrev_b32_e32 v129, 1, v138
	v_lshrrev_b32_e32 v130, 2, v138
	v_and_or_b32 v128, v138, 15, v128
	v_and_b32_e32 v129, 0x60, v129
	v_and_b32_e32 v130, 12, v130
	v_or3_b32 v130, v129, v130, s20
	v_ashrrev_i32_e32 v129, 31, v128
	v_ashrrev_i32_e32 v131, 31, v130
	v_lshlrev_b64 v[132:133], 13, v[128:129]
	v_lshlrev_b64 v[130:131], 2, v[130:131]
	v_lshl_add_u64 v[132:133], v[132:133], 0, v[130:131]
	v_lshl_add_u64 v[134:135], s[8:9], 0, v[132:133]
	v_lshl_add_u64 v[136:137], s[8:9], 0, v[132:133]
	v_add_co_u32_e32 v140, vcc, 0x20000, v134
	s_nop 1
	v_addc_co_u32_e32 v141, vcc, 0, v135, vcc
	v_add_co_u32_e32 v144, vcc, 0x40000, v134
	s_nop 1
	v_addc_co_u32_e32 v145, vcc, 0, v135, vcc
	v_add_co_u32_e32 v128, vcc, 0x60000, v134
	s_nop 1
	v_addc_co_u32_e32 v129, vcc, 0, v135, vcc
	v_add_co_u32_e32 v142, vcc, 0x20000, v136
	s_nop 1
	v_addc_co_u32_e32 v143, vcc, 0, v137, vcc
	v_add_co_u32_e32 v146, vcc, 0x40000, v136
	s_nop 1
	v_addc_co_u32_e32 v147, vcc, 0, v137, vcc
	v_add_co_u32_e32 v130, vcc, 0x60000, v136
	s_nop 1
	v_addc_co_u32_e32 v131, vcc, 0, v137, vcc
	global_load_dwordx4 v[180:183], v[134:135], off offset:0
	global_load_dwordx4 v[184:187], v[134:135], off offset:64
	global_load_dwordx4 v[188:191], v[140:141], off offset:0
	global_load_dwordx4 v[192:195], v[140:141], off offset:64
	global_load_dwordx4 v[196:199], v[144:145], off offset:0
	global_load_dwordx4 v[200:203], v[144:145], off offset:64
	global_load_dwordx4 v[204:207], v[128:129], off offset:0
	global_load_dwordx4 v[208:211], v[128:129], off offset:64
	global_load_dwordx4 v[158:161], v[134:135], off offset:512
	global_load_dwordx4 v[162:165], v[134:135], off offset:576
	global_load_dwordx4 v[166:169], v[140:141], off offset:512
	global_load_dwordx4 v[170:173], v[140:141], off offset:576
	global_load_dwordx4 v[212:215], v[144:145], off offset:512
	global_load_dwordx4 v[216:219], v[144:145], off offset:576
	global_load_dwordx4 v[222:225], v[128:129], off offset:512
	global_load_dwordx4 v[226:229], v[128:129], off offset:576
	s_waitcnt vmcnt(8)
	v_pk_fma_f32 v[124:125], v[124:125], 0.5, v[180:181] op_sel_hi:[1,0,1]
	v_pk_fma_f32 v[126:127], v[126:127], 0.5, v[182:183] op_sel_hi:[1,0,1]
	v_pk_fma_f32 v[120:121], v[120:121], 0.5, v[184:185] op_sel_hi:[1,0,1]
	v_pk_fma_f32 v[122:123], v[122:123], 0.5, v[186:187] op_sel_hi:[1,0,1]
	v_pk_fma_f32 v[116:117], v[116:117], 0.5, v[188:189] op_sel_hi:[1,0,1]
	v_pk_fma_f32 v[118:119], v[118:119], 0.5, v[190:191] op_sel_hi:[1,0,1]
	v_pk_fma_f32 v[112:113], v[112:113], 0.5, v[192:193] op_sel_hi:[1,0,1]
	v_pk_fma_f32 v[114:115], v[114:115], 0.5, v[194:195] op_sel_hi:[1,0,1]
	v_pk_fma_f32 v[108:109], v[108:109], 0.5, v[196:197] op_sel_hi:[1,0,1]
	v_pk_fma_f32 v[110:111], v[110:111], 0.5, v[198:199] op_sel_hi:[1,0,1]
	v_pk_fma_f32 v[104:105], v[104:105], 0.5, v[200:201] op_sel_hi:[1,0,1]
	v_pk_fma_f32 v[106:107], v[106:107], 0.5, v[202:203] op_sel_hi:[1,0,1]
	v_pk_fma_f32 v[100:101], v[100:101], 0.5, v[204:205] op_sel_hi:[1,0,1]
	v_pk_fma_f32 v[102:103], v[102:103], 0.5, v[206:207] op_sel_hi:[1,0,1]
	v_pk_fma_f32 v[96:97], v[96:97], 0.5, v[208:209] op_sel_hi:[1,0,1]
	v_pk_fma_f32 v[98:99], v[98:99], 0.5, v[210:211] op_sel_hi:[1,0,1]
	global_store_dwordx4 v[136:137], v[124:127], off offset:0
	global_store_dwordx4 v[136:137], v[120:123], off offset:64
	global_store_dwordx4 v[142:143], v[116:119], off offset:0
	global_store_dwordx4 v[142:143], v[112:115], off offset:64
	global_store_dwordx4 v[146:147], v[108:111], off offset:0
	global_store_dwordx4 v[146:147], v[104:107], off offset:64
	global_store_dwordx4 v[130:131], v[100:103], off offset:0
	global_store_dwordx4 v[130:131], v[96:99], off offset:64
	v_add_co_u32_e32 v134, vcc, 0x100000, v134
	s_nop 1
	v_addc_co_u32_e32 v135, vcc, 0, v135, vcc
	v_add_co_u32_e32 v140, vcc, 0x100000, v140
	s_nop 1
	v_addc_co_u32_e32 v141, vcc, 0, v141, vcc
	v_add_co_u32_e32 v144, vcc, 0x100000, v144
	s_nop 1
	v_addc_co_u32_e32 v145, vcc, 0, v145, vcc
	v_add_co_u32_e32 v128, vcc, 0x100000, v128
	s_nop 1
	v_addc_co_u32_e32 v129, vcc, 0, v129, vcc
	global_load_dwordx4 v[180:183], v[134:135], off offset:0
	global_load_dwordx4 v[184:187], v[134:135], off offset:64
	global_load_dwordx4 v[188:191], v[140:141], off offset:0
	global_load_dwordx4 v[192:195], v[140:141], off offset:64
	global_load_dwordx4 v[196:199], v[144:145], off offset:0
	global_load_dwordx4 v[200:203], v[144:145], off offset:64
	global_load_dwordx4 v[204:207], v[128:129], off offset:0
	global_load_dwordx4 v[208:211], v[128:129], off offset:64
	s_waitcnt vmcnt(16)
; #define SCHED __builtin_amdgcn_sched_barrier(0)
; __device__ __forceinline__ void residual_epi(ACC_T, const float* __restrict__ xs, float* __restrict__ xo, float alpha,
;                                              int brow, int bcol, int wr, int wc, int fr, int fq) {
; #pragma unroll
;   for (int ai = 0; ai < 2; ++ai)
; #pragma unroll
;     for (int bj = 0; bj < 2; ++bj) {
;       float4 t[4][2];
;       size_t base = (size_t)(brow + ai * 128 + wr * 64 + fr) * 2048 + (bcol + bj * 128 + wc * 32 + fq * 4);
; #pragma unroll
;       for (int m = 0; m < 4; ++m)
; #pragma unroll
;         for (int n = 0; n < 2; ++n) t[m][n] = *(const float4*)(xs + base + (size_t)(m * 16) * 2048 + n * 16);
;       SCHED;
; #pragma unroll
;       for (int m = 0; m < 4; ++m)
; #pragma unroll
;         for (int n = 0; n < 2; ++n) {
;           f32x4 a = acc[ai][bj][m][n];
;           float4 o; o.x = t[m][n].x + alpha * a[0]; o.y = t[m][n].y + alpha * a[1]; o.z = t[m][n].z + alpha * a[2]; o.w = t[m][n].w + alpha * a[3];
;           *(float4*)(xo + base + (size_t)(m * 16) * 2048 + n * 16) = o;
;         }
;       SCHED;
;     }
; }
	v_pk_fma_f32 v[92:93], v[92:93], 0.5, v[158:159] op_sel_hi:[1,0,1]
	v_pk_fma_f32 v[94:95], v[94:95], 0.5, v[160:161] op_sel_hi:[1,0,1]
	v_pk_fma_f32 v[88:89], v[88:89], 0.5, v[162:163] op_sel_hi:[1,0,1]
	v_pk_fma_f32 v[90:91], v[90:91], 0.5, v[164:165] op_sel_hi:[1,0,1]
	v_pk_fma_f32 v[84:85], v[84:85], 0.5, v[166:167] op_sel_hi:[1,0,1]
	v_pk_fma_f32 v[86:87], v[86:87], 0.5, v[168:169] op_sel_hi:[1,0,1]
	v_pk_fma_f32 v[80:81], v[80:81], 0.5, v[170:171] op_sel_hi:[1,0,1]
	v_pk_fma_f32 v[82:83], v[82:83], 0.5, v[172:173] op_sel_hi:[1,0,1]
	v_pk_fma_f32 v[76:77], v[76:77], 0.5, v[212:213] op_sel_hi:[1,0,1]
	v_pk_fma_f32 v[78:79], v[78:79], 0.5, v[214:215] op_sel_hi:[1,0,1]
	v_pk_fma_f32 v[72:73], v[72:73], 0.5, v[216:217] op_sel_hi:[1,0,1]
	v_pk_fma_f32 v[74:75], v[74:75], 0.5, v[218:219] op_sel_hi:[1,0,1]
	v_pk_fma_f32 v[68:69], v[68:69], 0.5, v[222:223] op_sel_hi:[1,0,1]
	v_pk_fma_f32 v[70:71], v[70:71], 0.5, v[224:225] op_sel_hi:[1,0,1]
	v_pk_fma_f32 v[64:65], v[64:65], 0.5, v[226:227] op_sel_hi:[1,0,1]
	v_pk_fma_f32 v[66:67], v[66:67], 0.5, v[228:229] op_sel_hi:[1,0,1]
	global_store_dwordx4 v[136:137], v[92:95], off offset:512
	global_store_dwordx4 v[136:137], v[88:91], off offset:576
	global_store_dwordx4 v[142:143], v[84:87], off offset:512
	global_store_dwordx4 v[142:143], v[80:83], off offset:576
	global_store_dwordx4 v[146:147], v[76:79], off offset:512
	global_store_dwordx4 v[146:147], v[72:75], off offset:576
	global_store_dwordx4 v[130:131], v[68:71], off offset:512
	global_store_dwordx4 v[130:131], v[64:67], off offset:576
	global_load_dwordx4 v[158:161], v[134:135], off offset:512
	global_load_dwordx4 v[162:165], v[134:135], off offset:576
	global_load_dwordx4 v[166:169], v[140:141], off offset:512
	global_load_dwordx4 v[170:173], v[140:141], off offset:576
	global_load_dwordx4 v[212:215], v[144:145], off offset:512
	global_load_dwordx4 v[216:219], v[144:145], off offset:576
	global_load_dwordx4 v[222:225], v[128:129], off offset:512
	global_load_dwordx4 v[226:229], v[128:129], off offset:576
	v_add_co_u32_e32 v136, vcc, 0x100000, v136
	s_nop 1
	v_addc_co_u32_e32 v137, vcc, 0, v137, vcc
	v_add_co_u32_e32 v142, vcc, 0x100000, v142
	s_nop 1
	v_addc_co_u32_e32 v143, vcc, 0, v143, vcc
	v_add_co_u32_e32 v146, vcc, 0x100000, v146
	s_nop 1
	v_addc_co_u32_e32 v147, vcc, 0, v147, vcc
	v_add_co_u32_e32 v130, vcc, 0x100000, v130
	s_nop 1
	v_addc_co_u32_e32 v131, vcc, 0, v131, vcc
	s_waitcnt vmcnt(16)
	v_pk_fma_f32 v[60:61], v[60:61], 0.5, v[180:181] op_sel_hi:[1,0,1]
	v_pk_fma_f32 v[62:63], v[62:63], 0.5, v[182:183] op_sel_hi:[1,0,1]
	v_pk_fma_f32 v[56:57], v[56:57], 0.5, v[184:185] op_sel_hi:[1,0,1]
	v_pk_fma_f32 v[58:59], v[58:59], 0.5, v[186:187] op_sel_hi:[1,0,1]
	v_pk_fma_f32 v[52:53], v[52:53], 0.5, v[188:189] op_sel_hi:[1,0,1]
	v_pk_fma_f32 v[54:55], v[54:55], 0.5, v[190:191] op_sel_hi:[1,0,1]
	v_pk_fma_f32 v[48:49], v[48:49], 0.5, v[192:193] op_sel_hi:[1,0,1]
	v_pk_fma_f32 v[50:51], v[50:51], 0.5, v[194:195] op_sel_hi:[1,0,1]
	v_pk_fma_f32 v[44:45], v[44:45], 0.5, v[196:197] op_sel_hi:[1,0,1]
	v_pk_fma_f32 v[46:47], v[46:47], 0.5, v[198:199] op_sel_hi:[1,0,1]
	v_pk_fma_f32 v[40:41], v[40:41], 0.5, v[200:201] op_sel_hi:[1,0,1]
	v_pk_fma_f32 v[42:43], v[42:43], 0.5, v[202:203] op_sel_hi:[1,0,1]
	v_pk_fma_f32 v[36:37], v[36:37], 0.5, v[204:205] op_sel_hi:[1,0,1]
	v_pk_fma_f32 v[38:39], v[38:39], 0.5, v[206:207] op_sel_hi:[1,0,1]
	v_pk_fma_f32 v[32:33], v[32:33], 0.5, v[208:209] op_sel_hi:[1,0,1]
	v_pk_fma_f32 v[34:35], v[34:35], 0.5, v[210:211] op_sel_hi:[1,0,1]
	global_store_dwordx4 v[136:137], v[60:63], off offset:0
	global_store_dwordx4 v[136:137], v[56:59], off offset:64
	global_store_dwordx4 v[142:143], v[52:55], off offset:0
	global_store_dwordx4 v[142:143], v[48:51], off offset:64
	global_store_dwordx4 v[146:147], v[44:47], off offset:0
	global_store_dwordx4 v[146:147], v[40:43], off offset:64
	global_store_dwordx4 v[130:131], v[36:39], off offset:0
	global_store_dwordx4 v[130:131], v[32:35], off offset:64
	s_waitcnt vmcnt(8)
	v_pk_fma_f32 v[28:29], v[28:29], 0.5, v[158:159] op_sel_hi:[1,0,1]
	v_pk_fma_f32 v[30:31], v[30:31], 0.5, v[160:161] op_sel_hi:[1,0,1]
	v_pk_fma_f32 v[24:25], v[24:25], 0.5, v[162:163] op_sel_hi:[1,0,1]
	v_pk_fma_f32 v[26:27], v[26:27], 0.5, v[164:165] op_sel_hi:[1,0,1]
	v_pk_fma_f32 v[20:21], v[20:21], 0.5, v[166:167] op_sel_hi:[1,0,1]
	v_pk_fma_f32 v[22:23], v[22:23], 0.5, v[168:169] op_sel_hi:[1,0,1]
	v_pk_fma_f32 v[16:17], v[16:17], 0.5, v[170:171] op_sel_hi:[1,0,1]
	v_pk_fma_f32 v[18:19], v[18:19], 0.5, v[172:173] op_sel_hi:[1,0,1]
	v_pk_fma_f32 v[12:13], v[12:13], 0.5, v[212:213] op_sel_hi:[1,0,1]
	v_pk_fma_f32 v[14:15], v[14:15], 0.5, v[214:215] op_sel_hi:[1,0,1]
	v_pk_fma_f32 v[8:9], v[8:9], 0.5, v[216:217] op_sel_hi:[1,0,1]
	v_pk_fma_f32 v[10:11], v[10:11], 0.5, v[218:219] op_sel_hi:[1,0,1]
	v_pk_fma_f32 v[4:5], v[4:5], 0.5, v[222:223] op_sel_hi:[1,0,1]
	v_pk_fma_f32 v[6:7], v[6:7], 0.5, v[224:225] op_sel_hi:[1,0,1]
	v_pk_fma_f32 v[0:1], v[0:1], 0.5, v[226:227] op_sel_hi:[1,0,1]
	v_pk_fma_f32 v[2:3], v[2:3], 0.5, v[228:229] op_sel_hi:[1,0,1]
	global_store_dwordx4 v[136:137], v[28:31], off offset:512
	global_store_dwordx4 v[136:137], v[24:27], off offset:576
	global_store_dwordx4 v[142:143], v[20:23], off offset:512
	global_store_dwordx4 v[142:143], v[16:19], off offset:576
	global_store_dwordx4 v[146:147], v[12:15], off offset:512
	global_store_dwordx4 v[146:147], v[8:11], off offset:576
	global_store_dwordx4 v[130:131], v[4:7], off offset:512
	global_store_dwordx4 v[130:131], v[0:3], off offset:576
	s_mov_b32 s19, 0x60000
	s_andn2_b64 vcc, exec, s[12:13]
	s_mov_b32 s20, s22
	s_mov_b32 s19, s21
	s_cbranch_vccz .LBB0_2585
